# hand-scheduled GQA attention phase: software-pipelined QK/exp/PV blocks, 8-deep LDS fragment prefetch, same accumulation order
# speedup vs baseline: 1.1263x; 1.0168x over previous
.LBB0_22:
	s_cmp_eq_u32 s66, 6
	s_cbranch_scc0 .Lwt1_skip
	s_cmp_ge_u32 s99, 0x80
	s_cbranch_scc0 .Lwt1_skip
	s_load_dword vcc_lo, s[100:101], 0xc0
	s_waitcnt lgkmcnt(0)
	s_cmp_eq_u32 vcc_lo, 0x100
	s_cbranch_scc0 .Lwt1_skip
	s_mov_b64 exec, -1
	v_writelane_b32 v59, s16, 0
	v_writelane_b32 v59, s17, 1
	v_writelane_b32 v59, s18, 2
	v_writelane_b32 v59, s19, 3
	v_writelane_b32 v59, s20, 4
	v_writelane_b32 v59, s21, 5
	v_writelane_b32 v59, s22, 6
	v_writelane_b32 v59, s23, 7
	v_writelane_b32 v59, s24, 8
	v_writelane_b32 v59, s25, 9
	v_writelane_b32 v59, s26, 10
	v_writelane_b32 v59, s27, 11
	v_writelane_b32 v59, s28, 12
	v_writelane_b32 v59, s29, 13
	v_writelane_b32 v59, s30, 14
	v_writelane_b32 v59, s31, 15
	v_writelane_b32 v59, s32, 16
	v_writelane_b32 v59, s33, 17
	v_writelane_b32 v59, s34, 18
	v_writelane_b32 v59, s35, 19
	v_writelane_b32 v59, s36, 20
	v_writelane_b32 v59, s37, 21
	v_writelane_b32 v59, s38, 22
	v_writelane_b32 v59, s39, 23
	v_writelane_b32 v59, s40, 24
	v_writelane_b32 v59, s41, 25
	v_writelane_b32 v59, s42, 26
	v_writelane_b32 v59, s43, 27
	v_writelane_b32 v59, s44, 28
	v_writelane_b32 v59, s45, 29
	v_writelane_b32 v59, s46, 30
	v_writelane_b32 v59, s47, 31
	v_writelane_b32 v59, s48, 32
	v_writelane_b32 v59, s49, 33
	v_writelane_b32 v59, s50, 34
	v_writelane_b32 v59, s51, 35
	v_writelane_b32 v59, s52, 36
	v_writelane_b32 v59, s53, 37
	v_writelane_b32 v59, s54, 38
	v_writelane_b32 v59, s55, 39
	s_memrealtime s[40:41]
	s_waitcnt lgkmcnt(0)
	s_add_u32 s42, s40, 1000

.LBB0_818:
	s_and_b64 vcc, exec, s[0:1]
	s_cbranch_vccz .LBB0_840
	s_mov_b64 exec, -1
	v_writelane_b32 v240, s0, 0
	v_writelane_b32 v240, s1, 1
	v_writelane_b32 v240, s2, 2
	v_writelane_b32 v240, s3, 3
	v_writelane_b32 v240, s4, 4
	v_writelane_b32 v240, s5, 5
	v_writelane_b32 v240, s6, 6
	v_writelane_b32 v240, s7, 7
	v_writelane_b32 v240, s8, 8
	v_writelane_b32 v240, s9, 9
	v_writelane_b32 v240, s10, 10
	v_writelane_b32 v240, s11, 11
	v_writelane_b32 v240, s12, 12
	v_writelane_b32 v240, s13, 13
	v_writelane_b32 v240, s14, 14
	v_writelane_b32 v240, s15, 15
	v_writelane_b32 v240, s16, 16
	v_writelane_b32 v240, s17, 17
	v_writelane_b32 v240, s18, 18
	v_writelane_b32 v240, s19, 19
	v_writelane_b32 v240, s20, 20
	v_writelane_b32 v240, s21, 21
	v_writelane_b32 v240, s22, 22
	v_writelane_b32 v240, s23, 23
	v_writelane_b32 v240, s24, 24
	v_writelane_b32 v240, s25, 25
	v_writelane_b32 v240, s26, 26
	v_writelane_b32 v240, s27, 27
	v_writelane_b32 v240, s28, 28
	v_writelane_b32 v240, s29, 29
	v_writelane_b32 v240, s30, 30
	v_writelane_b32 v240, s31, 31
	v_writelane_b32 v240, s32, 32
	v_writelane_b32 v240, s33, 33
	v_writelane_b32 v240, s34, 34
	v_writelane_b32 v240, s35, 35
	v_writelane_b32 v240, s36, 36
	v_writelane_b32 v240, s37, 37
	v_writelane_b32 v240, s38, 38
	v_writelane_b32 v240, s39, 39
	v_writelane_b32 v240, s40, 40
	v_writelane_b32 v240, s41, 41
	v_writelane_b32 v240, s42, 42
	v_writelane_b32 v240, s43, 43
	v_writelane_b32 v240, s44, 44
	v_writelane_b32 v240, s45, 45
	v_writelane_b32 v240, s46, 46
	v_writelane_b32 v240, s47, 47
	v_writelane_b32 v240, s48, 48
	v_writelane_b32 v240, s49, 49
	v_writelane_b32 v240, s50, 50
	v_writelane_b32 v240, s51, 51
	v_writelane_b32 v240, s52, 52
	v_writelane_b32 v240, s53, 53
	v_writelane_b32 v240, s54, 54
	v_writelane_b32 v240, s55, 55
	v_lshrrev_b32_e32 v144, 6, v225
	v_and_b32_e32 v241, 63, v225
	s_load_dwordx2 s[10:11], s[100:101], 0xb0
	s_load_dwordx2 s[12:13], s[100:101], 0x78
	s_load_dwordx2 s[14:15], s[100:101], 0x80
	v_readfirstlane_b32 s4, v144
	v_lshlrev_b32_e32 v244, 2, v241
	s_waitcnt lgkmcnt(0)
	global_load_dword v245, v244, s[12:13]
	global_load_dword v246, v244, s[14:15]
	v_and_b32_e32 v247, 15, v241
	v_lshrrev_b32_e32 v248, 4, v241
	v_bfe_u32 v249, v241, 1, 3
	v_xor_b32_e32 v249, v249, v248
	v_lshlrev_b32_e32 v249, 4, v249
	v_lshl_or_b32 v220, v247, 7, v249
	v_xor_b32_e32 v221, 64, v220
	v_xor_b32_e32 v249, v248, v247
	v_lshlrev_b32_e32 v249, 4, v249
	v_lshl_or_b32 v222, v247, 8, v249
	v_xor_b32_e32 v223, 64, v222
	v_xor_b32_e32 v232, 0x80, v222
	v_xor_b32_e32 v233, 0xc0, v222
	s_lshl_b32 s20, s4, 4
	v_lshrrev_b32_e32 v249, 3, v241
	v_add_u32_e32 v249, s20, v249
	v_and_b32_e32 v250, 7, v241
	v_bfe_u32 v251, v249, 1, 3
	v_xor_b32_e32 v251, v251, v250
	v_lshlrev_b32_e32 v251, 4, v251
	v_lshl_or_b32 v234, v249, 9, v251
	v_add_u32_e32 v249, 8, v249
	v_bfe_u32 v251, v249, 1, 3
	v_xor_b32_e32 v251, v251, v250
	v_lshlrev_b32_e32 v251, 4, v251
	v_lshl_or_b32 v235, v249, 9, v251
	s_lshl_b32 s20, s4, 3
	v_add_u32_e32 v249, s20, v248
	v_and_b32_e32 v251, 15, v249
	v_xor_b32_e32 v251, v251, v247
	v_lshlrev_b32_e32 v251, 4, v251
	v_lshl_or_b32 v236, v249, 12, v251
	v_add_u32_e32 v249, 4, v249
	v_and_b32_e32 v251, 15, v249
	v_xor_b32_e32 v251, v251, v247
	v_lshlrev_b32_e32 v251, 4, v251
	v_lshl_or_b32 v237, v249, 12, v251
	v_lshlrev_b32_e32 v249, 11, v247
	v_lshl_add_u32 v178, v248, 4, v249
	v_lshl_add_u32 v179, v248, 3, v249
	v_mov_b32_e32 v212, 0x3f803f80
	v_mov_b32_e32 v213, v212
	v_mov_b32_e32 v214, v212
	v_mov_b32_e32 v215, v212
	s_waitcnt vmcnt(0)
	v_and_b32_e32 v245, 0x7fffffff, v245
	v_and_b32_e32 v246, 0x7fffffff, v246
	v_xor_b32_e32 v249, 32, v241
	v_lshlrev_b32_e32 v249, 2, v249
	ds_bpermute_b32 v250, v249, v245
	ds_bpermute_b32 v251, v249, v246
	s_waitcnt lgkmcnt(0)
	v_max_f32_e32 v245, v245, v250
	v_max_f32_e32 v246, v246, v251
	v_xor_b32_e32 v249, 16, v241
	v_lshlrev_b32_e32 v249, 2, v249
	ds_bpermute_b32 v250, v249, v245
	ds_bpermute_b32 v251, v249, v246
	s_waitcnt lgkmcnt(0)
	v_max_f32_e32 v245, v245, v250
	v_max_f32_e32 v246, v246, v251
	v_xor_b32_e32 v249, 8, v241
	v_lshlrev_b32_e32 v249, 2, v249
	ds_bpermute_b32 v250, v249, v245
	ds_bpermute_b32 v251, v249, v246
	s_waitcnt lgkmcnt(0)
	v_max_f32_e32 v245, v245, v250
	v_max_f32_e32 v246, v246, v251
	v_xor_b32_e32 v249, 4, v241
	v_lshlrev_b32_e32 v249, 2, v249
	ds_bpermute_b32 v250, v249, v245
	ds_bpermute_b32 v251, v249, v246
	s_waitcnt lgkmcnt(0)
	v_max_f32_e32 v245, v245, v250
	v_max_f32_e32 v246, v246, v251
	v_xor_b32_e32 v249, 2, v241
	v_lshlrev_b32_e32 v249, 2, v249
	ds_bpermute_b32 v250, v249, v245
	ds_bpermute_b32 v251, v249, v246
	s_waitcnt lgkmcnt(0)
	v_max_f32_e32 v245, v245, v250
	v_max_f32_e32 v246, v246, v251
	v_xor_b32_e32 v249, 1, v241
	v_lshlrev_b32_e32 v249, 2, v249
	ds_bpermute_b32 v250, v249, v245
	ds_bpermute_b32 v251, v249, v246
	s_waitcnt lgkmcnt(0)
	v_max_f32_e32 v245, v245, v250
	v_max_f32_e32 v246, v246, v251
	v_mul_f32_e32 v245, 0x41000000, v245
	v_mul_f32_e32 v245, v245, v246
	v_mul_f32_e32 v245, 0x3fb8aa3b, v245
	v_xor_b32_e32 v216, 0x80000000, v245
	v_mov_b32_e32 v217, v216
	v_mov_b32_e32 v218, v216
	v_mov_b32_e32 v219, v216
	s_lshl_b32 s22, s4, 11
	s_add_u32 s22, s22, 16
	s_mov_b32 s6, 0
.Lgq_tile:
	s_and_b32 s20, s99, 7
	s_lshl_b32 s20, s20, 1
	s_lshr_b32 s21, s99, 7
	s_add_u32 s20, s20, s21
	s_lshl_b32 s21, s6, 4
	s_add_u32 s20, s20, s21
	s_lshl_b32 s20, s20, 4
	s_bfe_u32 s21, s99, 0x40003
	s_add_u32 s5, s20, s21
	s_and_b32 s23, s5, 3
	s_bfe_u32 s24, s5, 0x20002
	s_bfe_u32 s25, s5, 0x20004
	s_lshr_b32 s26, s5, 6
	s_lshl_b32 s27, s25, 2
	s_add_u32 s27, s27, s23
	s_lshl_b32 s28, s26, 11
	s_lshl_b32 s29, s24, 9
	s_add_u32 s28, s28, s29
	s_lshl_b32 s29, s4, 6
	s_add_u32 s28, s28, s29
	s_lshl_b32 s29, s28, 11
	s_lshl_b32 s30, s27, 7
	s_add_u32 s29, s29, s30
	s_add_u32 s16, s10, 0x7200000
	s_addc_u32 s17, s11, 0
	s_add_u32 s16, s16, s29
	s_addc_u32 s17, s17, 0
	s_add_u32 s18, s10, 0xa200000
	s_addc_u32 s19, s11, 0
	s_add_u32 s18, s18, s29
	s_addc_u32 s19, s19, 0
	s_lshl_b32 s29, s26, 20
	s_lshl_b32 s30, s25, 7
	s_add_u32 s29, s29, s30
	s_add_u32 s0, s10, 0x9200000
	s_addc_u32 s1, s11, 0
	s_add_u32 s0, s0, s29
	s_addc_u32 s1, s1, 0
	s_lshl_b32 s29, s26, 2
	s_add_u32 s29, s29, s25
	s_lshl_b32 s29, s29, 18
	s_add_u32 s2, s10, 0x9a00000
	s_addc_u32 s3, s11, 0
	s_add_u32 s2, s2, s29
	s_addc_u32 s3, s3, 0
	s_waitcnt vmcnt(0) lgkmcnt(0)
	s_barrier
	s_mov_b64 s[30:31], s[16:17]
	global_load_dwordx4 v[0:3], v178, s[30:31]
	global_load_dwordx4 v[4:7], v178, s[30:31] offset:64
	s_add_u32 s30, s30, 0x8000
	s_addc_u32 s31, s31, 0
	global_load_dwordx4 v[8:11], v178, s[30:31]
	global_load_dwordx4 v[12:15], v178, s[30:31] offset:64
	s_add_u32 s30, s30, 0x8000
	s_addc_u32 s31, s31, 0
	global_load_dwordx4 v[16:19], v178, s[30:31]
	global_load_dwordx4 v[20:23], v178, s[30:31] offset:64
	s_add_u32 s30, s30, 0x8000
	s_addc_u32 s31, s31, 0
	global_load_dwordx4 v[24:27], v178, s[30:31]
	global_load_dwordx4 v[28:31], v178, s[30:31] offset:64
	s_mov_b32 s8, 0
	s_lshl_b32 s20, s8, 15
	s_add_u32 s20, s20, s22
	s_mov_b32 m0, s20
	s_add_u32 s21, s20, 0x400
	global_load_lds_dwordx4 v234, s[0:1]
	s_mov_b32 m0, s21
	s_add_u32 s21, s20, 0x4000
	global_load_lds_dwordx4 v235, s[0:1]
	s_mov_b32 m0, s21
	s_add_u32 s21, s20, 0x4400
	global_load_lds_dwordx4 v236, s[2:3]
	s_mov_b32 m0, s21
	s_add_u32 s0, s0, 0x10000
	global_load_lds_dwordx4 v237, s[2:3]
	s_addc_u32 s1, s1, 0
	s_add_u32 s2, s2, 0x100
	s_addc_u32 s3, s3, 0
	s_add_u32 s8, s8, 1
	s_and_b32 s8, s8, 3
	s_lshl_b32 s20, s8, 15
	s_add_u32 s20, s20, s22
	s_mov_b32 m0, s20
	s_add_u32 s21, s20, 0x400
	global_load_lds_dwordx4 v234, s[0:1]
	s_mov_b32 m0, s21
	s_add_u32 s21, s20, 0x4000
	global_load_lds_dwordx4 v235, s[0:1]
	s_mov_b32 m0, s21
	s_add_u32 s21, s20, 0x4400
	global_load_lds_dwordx4 v236, s[2:3]
	s_mov_b32 m0, s21
	s_add_u32 s0, s0, 0x10000
	global_load_lds_dwordx4 v237, s[2:3]
	s_addc_u32 s1, s1, 0
	s_add_u32 s2, s2, 0x100
	s_addc_u32 s3, s3, 0
	s_add_u32 s8, s8, 1
	s_and_b32 s8, s8, 3
	v_mov_b32_e32 v32, 0
	v_mov_b32_e32 v33, 0
	v_mov_b32_e32 v34, 0
	v_mov_b32_e32 v35, 0
	v_mov_b32_e32 v36, 0
	v_mov_b32_e32 v37, 0
	v_mov_b32_e32 v38, 0
	v_mov_b32_e32 v39, 0
	v_mov_b32_e32 v40, 0
	v_mov_b32_e32 v41, 0
	v_mov_b32_e32 v42, 0
	v_mov_b32_e32 v43, 0
	v_mov_b32_e32 v44, 0
	v_mov_b32_e32 v45, 0
	v_mov_b32_e32 v46, 0
	v_mov_b32_e32 v47, 0
	v_mov_b32_e32 v48, 0
	v_mov_b32_e32 v49, 0
	v_mov_b32_e32 v50, 0
	v_mov_b32_e32 v51, 0
	v_mov_b32_e32 v52, 0
	v_mov_b32_e32 v53, 0
	v_mov_b32_e32 v54, 0
	v_mov_b32_e32 v55, 0
	v_mov_b32_e32 v56, 0
	v_mov_b32_e32 v57, 0
	v_mov_b32_e32 v58, 0
	v_mov_b32_e32 v59, 0
	v_mov_b32_e32 v60, 0
	v_mov_b32_e32 v61, 0
	v_mov_b32_e32 v62, 0
	v_mov_b32_e32 v63, 0
	v_mov_b32_e32 v64, 0
	v_mov_b32_e32 v65, 0
	v_mov_b32_e32 v66, 0
	v_mov_b32_e32 v67, 0
	v_mov_b32_e32 v68, 0
	v_mov_b32_e32 v69, 0
	v_mov_b32_e32 v70, 0
	v_mov_b32_e32 v71, 0
	v_mov_b32_e32 v72, 0
	v_mov_b32_e32 v73, 0
	v_mov_b32_e32 v74, 0
	v_mov_b32_e32 v75, 0
	v_mov_b32_e32 v76, 0
	v_mov_b32_e32 v77, 0
	v_mov_b32_e32 v78, 0
	v_mov_b32_e32 v79, 0
	v_mov_b32_e32 v80, 0
	v_mov_b32_e32 v81, 0
	v_mov_b32_e32 v82, 0
	v_mov_b32_e32 v83, 0
	v_mov_b32_e32 v84, 0
	v_mov_b32_e32 v85, 0
	v_mov_b32_e32 v86, 0
	v_mov_b32_e32 v87, 0
	v_mov_b32_e32 v88, 0
	v_mov_b32_e32 v89, 0
	v_mov_b32_e32 v90, 0
	v_mov_b32_e32 v91, 0
	v_mov_b32_e32 v92, 0
	v_mov_b32_e32 v93, 0
	v_mov_b32_e32 v94, 0
	v_mov_b32_e32 v95, 0
	v_mov_b32_e32 v96, 0
	v_mov_b32_e32 v97, 0
	v_mov_b32_e32 v98, 0
	v_mov_b32_e32 v99, 0
	v_mov_b32_e32 v100, 0
	v_mov_b32_e32 v101, 0
	v_mov_b32_e32 v102, 0
	v_mov_b32_e32 v103, 0
	v_mov_b32_e32 v104, 0
	v_mov_b32_e32 v105, 0
	v_mov_b32_e32 v106, 0
	v_mov_b32_e32 v107, 0
	v_mov_b32_e32 v108, 0
	v_mov_b32_e32 v109, 0
	v_mov_b32_e32 v110, 0
	v_mov_b32_e32 v111, 0
	v_and_b32_e32 v220, 0x7fff, v220
	v_and_b32_e32 v221, 0x7fff, v221
	v_and_b32_e32 v222, 0x7fff, v222
	v_and_b32_e32 v223, 0x7fff, v223
	v_and_b32_e32 v232, 0x7fff, v232
	v_and_b32_e32 v233, 0x7fff, v233
	s_waitcnt vmcnt(4)
	s_barrier
	s_lshl_b32 s20, s8, 15
	s_add_u32 s20, s20, s22
	s_mov_b32 m0, s20
	s_add_u32 s21, s20, 0x400
	global_load_lds_dwordx4 v234, s[0:1]
	s_mov_b32 m0, s21
	s_add_u32 s21, s20, 0x4000
	global_load_lds_dwordx4 v235, s[0:1]
	s_mov_b32 m0, s21
	s_add_u32 s21, s20, 0x4400
	global_load_lds_dwordx4 v236, s[2:3]
	s_mov_b32 m0, s21
	s_add_u32 s0, s0, 0x10000
	global_load_lds_dwordx4 v237, s[2:3]
	s_addc_u32 s1, s1, 0
	s_add_u32 s2, s2, 0x100
	s_addc_u32 s3, s3, 0
	s_add_u32 s8, s8, 1
	s_and_b32 s8, s8, 3
	ds_read_b128 v[180:183], v220 offset:16
	ds_read_b128 v[184:187], v221 offset:16
	ds_read_b128 v[188:191], v220 offset:2064
	ds_read_b128 v[192:195], v221 offset:2064
	ds_read_b128 v[196:199], v220 offset:4112
	ds_read_b128 v[200:203], v221 offset:4112
	ds_read_b128 v[204:207], v220 offset:6160
	ds_read_b128 v[208:211], v221 offset:6160
	s_waitcnt lgkmcnt(7)
	v_mfma_f32_16x16x32_bf16 v[112:115], v[180:183], v[0:3], v[216:219]
	v_mfma_f32_16x16x32_bf16 v[116:119], v[180:183], v[8:11], v[216:219]
	s_waitcnt lgkmcnt(6)
	v_mfma_f32_16x16x32_bf16 v[112:115], v[184:187], v[4:7], v[112:115]
	v_mfma_f32_16x16x32_bf16 v[116:119], v[184:187], v[12:15], v[116:119]
	s_waitcnt lgkmcnt(5)
	v_mfma_f32_16x16x32_bf16 v[120:123], v[188:191], v[0:3], v[216:219]
	v_mfma_f32_16x16x32_bf16 v[124:127], v[188:191], v[8:11], v[216:219]
	s_waitcnt lgkmcnt(4)
	v_mfma_f32_16x16x32_bf16 v[120:123], v[192:195], v[4:7], v[120:123]
	v_mfma_f32_16x16x32_bf16 v[124:127], v[192:195], v[12:15], v[124:127]
	s_waitcnt lgkmcnt(3)
	v_mfma_f32_16x16x32_bf16 v[128:131], v[196:199], v[0:3], v[216:219]
	v_mfma_f32_16x16x32_bf16 v[132:135], v[196:199], v[8:11], v[216:219]
	s_waitcnt lgkmcnt(2)
	v_mfma_f32_16x16x32_bf16 v[128:131], v[200:203], v[4:7], v[128:131]
	v_mfma_f32_16x16x32_bf16 v[132:135], v[200:203], v[12:15], v[132:135]
	s_waitcnt lgkmcnt(1)
	v_mfma_f32_16x16x32_bf16 v[136:139], v[204:207], v[0:3], v[216:219]
	v_mfma_f32_16x16x32_bf16 v[140:143], v[204:207], v[8:11], v[216:219]
	s_waitcnt lgkmcnt(0)
	v_mfma_f32_16x16x32_bf16 v[136:139], v[208:211], v[4:7], v[136:139]
	v_mfma_f32_16x16x32_bf16 v[140:143], v[208:211], v[12:15], v[140:143]
	ds_read_b128 v[180:183], v220 offset:16
	v_exp_f32_e32 v112, v112
	v_exp_f32_e32 v113, v113
	v_exp_f32_e32 v114, v114
	ds_read_b128 v[184:187], v221 offset:16
	v_exp_f32_e32 v115, v115
	v_exp_f32_e32 v116, v116
	v_exp_f32_e32 v117, v117
	ds_read_b128 v[188:191], v220 offset:2064
	v_exp_f32_e32 v118, v118
	v_exp_f32_e32 v119, v119
	v_exp_f32_e32 v120, v120
	ds_read_b128 v[192:195], v221 offset:2064
	v_exp_f32_e32 v121, v121
	v_exp_f32_e32 v122, v122
	v_exp_f32_e32 v123, v123
	ds_read_b128 v[196:199], v220 offset:4112
	v_exp_f32_e32 v124, v124
	v_exp_f32_e32 v125, v125
	v_exp_f32_e32 v126, v126
	ds_read_b128 v[200:203], v221 offset:4112
	v_exp_f32_e32 v127, v127
	v_cvt_pk_bf16_f32 v146, v112, v113
	v_cvt_pk_bf16_f32 v147, v114, v115
	ds_read_b128 v[204:207], v220 offset:6160
	v_cvt_pk_bf16_f32 v154, v116, v117
	v_cvt_pk_bf16_f32 v155, v118, v119
	v_cvt_pk_bf16_f32 v148, v120, v121
	ds_read_b128 v[208:211], v221 offset:6160
	v_cvt_pk_bf16_f32 v149, v122, v123
	v_cvt_pk_bf16_f32 v156, v124, v125
	v_cvt_pk_bf16_f32 v157, v126, v127
	s_waitcnt lgkmcnt(7)
	v_mfma_f32_16x16x32_bf16 v[112:115], v[180:183], v[16:19], v[216:219]
	v_exp_f32_e32 v128, v128
	v_exp_f32_e32 v129, v129
	v_mfma_f32_16x16x32_bf16 v[116:119], v[180:183], v[24:27], v[216:219]
	v_exp_f32_e32 v130, v130
	v_exp_f32_e32 v131, v131
	ds_read_b128 v[180:183], v222 offset:16400
	s_waitcnt lgkmcnt(7)
	v_mfma_f32_16x16x32_bf16 v[112:115], v[184:187], v[20:23], v[112:115]
	v_exp_f32_e32 v132, v132
	v_exp_f32_e32 v133, v133
	v_mfma_f32_16x16x32_bf16 v[116:119], v[184:187], v[28:31], v[116:119]
	v_exp_f32_e32 v134, v134
	v_exp_f32_e32 v135, v135
	ds_read_b128 v[184:187], v222 offset:20496
	s_waitcnt lgkmcnt(7)
	v_mfma_f32_16x16x32_bf16 v[120:123], v[188:191], v[16:19], v[216:219]
	v_exp_f32_e32 v136, v136
	v_exp_f32_e32 v137, v137
	v_cvt_pk_bf16_f32 v150, v128, v129
	v_mfma_f32_16x16x32_bf16 v[124:127], v[188:191], v[24:27], v[216:219]
	v_exp_f32_e32 v138, v138
	v_exp_f32_e32 v139, v139
	v_cvt_pk_bf16_f32 v151, v130, v131
	ds_read_b128 v[188:191], v222 offset:24592
	s_waitcnt lgkmcnt(7)
	v_mfma_f32_16x16x32_bf16 v[120:123], v[192:195], v[20:23], v[120:123]
	v_exp_f32_e32 v140, v140
	v_exp_f32_e32 v141, v141
	v_cvt_pk_bf16_f32 v158, v132, v133
	v_mfma_f32_16x16x32_bf16 v[124:127], v[192:195], v[28:31], v[124:127]
	v_exp_f32_e32 v142, v142
	v_exp_f32_e32 v143, v143
	v_cvt_pk_bf16_f32 v159, v134, v135
	ds_read_b128 v[192:195], v222 offset:28688
	s_waitcnt lgkmcnt(7)
	v_mfma_f32_16x16x32_bf16 v[128:131], v[196:199], v[16:19], v[216:219]
	v_cvt_pk_bf16_f32 v152, v136, v137
	v_mfma_f32_16x16x32_bf16 v[132:135], v[196:199], v[24:27], v[216:219]
	v_cvt_pk_bf16_f32 v153, v138, v139
	ds_read_b128 v[196:199], v223 offset:16400
	s_waitcnt lgkmcnt(7)
	v_mfma_f32_16x16x32_bf16 v[128:131], v[200:203], v[20:23], v[128:131]
	v_cvt_pk_bf16_f32 v160, v140, v141
	v_mfma_f32_16x16x32_bf16 v[132:135], v[200:203], v[28:31], v[132:135]
	v_cvt_pk_bf16_f32 v161, v142, v143
	ds_read_b128 v[200:203], v223 offset:20496
	s_waitcnt lgkmcnt(7)
	v_mfma_f32_16x16x32_bf16 v[136:139], v[204:207], v[16:19], v[216:219]
	v_mfma_f32_16x16x32_bf16 v[140:143], v[204:207], v[24:27], v[216:219]
	ds_read_b128 v[204:207], v223 offset:24592
	s_waitcnt lgkmcnt(7)
	v_mfma_f32_16x16x32_bf16 v[136:139], v[208:211], v[20:23], v[136:139]
	v_mfma_f32_16x16x32_bf16 v[140:143], v[208:211], v[28:31], v[140:143]
	ds_read_b128 v[208:211], v223 offset:28688
	s_mov_b32 s7, 0
	s_branch .Lgq_step1
.Lgq_loop:
	s_waitcnt lgkmcnt(7)
	v_mfma_f32_16x16x32_bf16 v[40:43], v[180:183], v[162:165], v[40:43]
	v_exp_f32_e32 v112, v112
	v_mfma_f32_16x16x32_bf16 v[44:47], v[180:183], v[170:173], v[44:47]
	v_exp_f32_e32 v113, v113
	ds_read_b128 v[180:183], v220 offset:16
	s_waitcnt lgkmcnt(7)
	v_mfma_f32_16x16x32_bf16 v[56:59], v[184:187], v[162:165], v[56:59]
	v_exp_f32_e32 v114, v114
	v_mfma_f32_16x16x32_bf16 v[60:63], v[184:187], v[170:173], v[60:63]
	v_exp_f32_e32 v115, v115
	ds_read_b128 v[184:187], v221 offset:16
	s_waitcnt lgkmcnt(7)
	v_mfma_f32_16x16x32_bf16 v[72:75], v[188:191], v[162:165], v[72:75]
	v_exp_f32_e32 v116, v116
	v_exp_f32_e32 v117, v117
	v_mfma_f32_16x16x32_bf16 v[76:79], v[188:191], v[170:173], v[76:79]
	v_exp_f32_e32 v118, v118
	ds_read_b128 v[188:191], v220 offset:2064
	s_waitcnt lgkmcnt(7)
	v_mfma_f32_16x16x32_bf16 v[88:91], v[192:195], v[162:165], v[88:91]
	v_exp_f32_e32 v119, v119
	v_mfma_f32_16x16x32_bf16 v[92:95], v[192:195], v[170:173], v[92:95]
	v_exp_f32_e32 v120, v120
	ds_read_b128 v[192:195], v221 offset:2064
	v_mfma_f32_16x16x32_bf16 v[104:107], v[212:215], v[162:165], v[104:107]
	v_exp_f32_e32 v121, v121
	v_mfma_f32_16x16x32_bf16 v[108:111], v[212:215], v[170:173], v[108:111]
	v_exp_f32_e32 v122, v122
	v_exp_f32_e32 v123, v123
	s_waitcnt lgkmcnt(7)
	v_mfma_f32_16x16x32_bf16 v[40:43], v[196:199], v[166:169], v[40:43]
	v_exp_f32_e32 v124, v124
	v_mfma_f32_16x16x32_bf16 v[44:47], v[196:199], v[174:177], v[44:47]
	v_exp_f32_e32 v125, v125
	ds_read_b128 v[196:199], v220 offset:4112
	s_waitcnt lgkmcnt(7)
	v_mfma_f32_16x16x32_bf16 v[56:59], v[200:203], v[166:169], v[56:59]
	v_exp_f32_e32 v126, v126
	v_mfma_f32_16x16x32_bf16 v[60:63], v[200:203], v[174:177], v[60:63]
	v_exp_f32_e32 v127, v127
	ds_read_b128 v[200:203], v221 offset:4112
	s_waitcnt lgkmcnt(7)
	v_mfma_f32_16x16x32_bf16 v[72:75], v[204:207], v[166:169], v[72:75]
	v_cvt_pk_bf16_f32 v146, v112, v113
	v_cvt_pk_bf16_f32 v147, v114, v115
	v_mfma_f32_16x16x32_bf16 v[76:79], v[204:207], v[174:177], v[76:79]
	v_cvt_pk_bf16_f32 v154, v116, v117
	ds_read_b128 v[204:207], v220 offset:6160
	s_waitcnt lgkmcnt(7)
	v_mfma_f32_16x16x32_bf16 v[88:91], v[208:211], v[166:169], v[88:91]
	v_cvt_pk_bf16_f32 v155, v118, v119
	v_mfma_f32_16x16x32_bf16 v[92:95], v[208:211], v[174:177], v[92:95]
	v_cvt_pk_bf16_f32 v148, v120, v121
	ds_read_b128 v[208:211], v221 offset:6160
	v_mfma_f32_16x16x32_bf16 v[104:107], v[212:215], v[166:169], v[104:107]
	v_cvt_pk_bf16_f32 v149, v122, v123
	v_mfma_f32_16x16x32_bf16 v[108:111], v[212:215], v[174:177], v[108:111]
	v_cvt_pk_bf16_f32 v156, v124, v125
	v_cvt_pk_bf16_f32 v157, v126, v127
	v_add_u32_e32 v222, 0x8000, v222
	v_and_b32_e32 v222, 0x1ffff, v222
	v_add_u32_e32 v223, 0x8000, v223
	v_and_b32_e32 v223, 0x1ffff, v223
	v_add_u32_e32 v232, 0x8000, v232
	v_and_b32_e32 v232, 0x1ffff, v232
	v_add_u32_e32 v233, 0x8000, v233
	v_and_b32_e32 v233, 0x1ffff, v233
	s_waitcnt lgkmcnt(7)
	v_mfma_f32_16x16x32_bf16 v[112:115], v[180:183], v[16:19], v[216:219]
	v_exp_f32_e32 v128, v128
	v_exp_f32_e32 v129, v129
	v_mfma_f32_16x16x32_bf16 v[116:119], v[180:183], v[24:27], v[216:219]
	v_exp_f32_e32 v130, v130
	v_exp_f32_e32 v131, v131
	ds_read_b128 v[180:183], v222 offset:16400
	s_waitcnt lgkmcnt(7)
	v_mfma_f32_16x16x32_bf16 v[112:115], v[184:187], v[20:23], v[112:115]
	v_exp_f32_e32 v132, v132
	v_exp_f32_e32 v133, v133
	v_mfma_f32_16x16x32_bf16 v[116:119], v[184:187], v[28:31], v[116:119]
	v_exp_f32_e32 v134, v134
	v_exp_f32_e32 v135, v135
	ds_read_b128 v[184:187], v222 offset:20496
	s_waitcnt lgkmcnt(7)
	v_mfma_f32_16x16x32_bf16 v[120:123], v[188:191], v[16:19], v[216:219]
	v_exp_f32_e32 v136, v136
	v_exp_f32_e32 v137, v137
	v_cvt_pk_bf16_f32 v150, v128, v129
	v_mfma_f32_16x16x32_bf16 v[124:127], v[188:191], v[24:27], v[216:219]
	v_exp_f32_e32 v138, v138
	v_exp_f32_e32 v139, v139
	v_cvt_pk_bf16_f32 v151, v130, v131
	ds_read_b128 v[188:191], v222 offset:24592
	s_waitcnt lgkmcnt(7)
	v_mfma_f32_16x16x32_bf16 v[120:123], v[192:195], v[20:23], v[120:123]
	v_exp_f32_e32 v140, v140
	v_exp_f32_e32 v141, v141
	v_cvt_pk_bf16_f32 v158, v132, v133
	v_mfma_f32_16x16x32_bf16 v[124:127], v[192:195], v[28:31], v[124:127]
	v_exp_f32_e32 v142, v142
	v_exp_f32_e32 v143, v143
	v_cvt_pk_bf16_f32 v159, v134, v135
	ds_read_b128 v[192:195], v222 offset:28688
	s_waitcnt lgkmcnt(7)
	v_mfma_f32_16x16x32_bf16 v[128:131], v[196:199], v[16:19], v[216:219]
	v_cvt_pk_bf16_f32 v152, v136, v137
	v_mfma_f32_16x16x32_bf16 v[132:135], v[196:199], v[24:27], v[216:219]
	v_cvt_pk_bf16_f32 v153, v138, v139
	ds_read_b128 v[196:199], v223 offset:16400
	s_waitcnt lgkmcnt(7)
	v_mfma_f32_16x16x32_bf16 v[128:131], v[200:203], v[20:23], v[128:131]
	v_cvt_pk_bf16_f32 v160, v140, v141
	v_mfma_f32_16x16x32_bf16 v[132:135], v[200:203], v[28:31], v[132:135]
	v_cvt_pk_bf16_f32 v161, v142, v143
	ds_read_b128 v[200:203], v223 offset:20496
	s_waitcnt lgkmcnt(7)
	v_mfma_f32_16x16x32_bf16 v[136:139], v[204:207], v[16:19], v[216:219]
	v_mfma_f32_16x16x32_bf16 v[140:143], v[204:207], v[24:27], v[216:219]
	ds_read_b128 v[204:207], v223 offset:24592
	s_waitcnt lgkmcnt(7)
	v_mfma_f32_16x16x32_bf16 v[136:139], v[208:211], v[20:23], v[136:139]
	v_mfma_f32_16x16x32_bf16 v[140:143], v[208:211], v[28:31], v[140:143]
	ds_read_b128 v[208:211], v223 offset:28688
.Lgq_step1:
	s_waitcnt lgkmcnt(7)
	v_mfma_f32_16x16x32_bf16 v[32:35], v[180:183], v[146:149], v[32:35]
	v_exp_f32_e32 v112, v112
	v_mfma_f32_16x16x32_bf16 v[36:39], v[180:183], v[154:157], v[36:39]
	v_exp_f32_e32 v113, v113
	ds_read_b128 v[180:183], v220 offset:8208
	s_waitcnt lgkmcnt(7)
	v_mfma_f32_16x16x32_bf16 v[48:51], v[184:187], v[146:149], v[48:51]
	v_exp_f32_e32 v114, v114
	v_mfma_f32_16x16x32_bf16 v[52:55], v[184:187], v[154:157], v[52:55]
	v_exp_f32_e32 v115, v115
	ds_read_b128 v[184:187], v221 offset:8208
	s_waitcnt lgkmcnt(7)
	v_mfma_f32_16x16x32_bf16 v[64:67], v[188:191], v[146:149], v[64:67]
	v_exp_f32_e32 v116, v116
	v_exp_f32_e32 v117, v117
	v_mfma_f32_16x16x32_bf16 v[68:71], v[188:191], v[154:157], v[68:71]
	v_exp_f32_e32 v118, v118
	ds_read_b128 v[188:191], v220 offset:10256
	s_waitcnt lgkmcnt(7)
	v_mfma_f32_16x16x32_bf16 v[80:83], v[192:195], v[146:149], v[80:83]
	v_exp_f32_e32 v119, v119
	v_mfma_f32_16x16x32_bf16 v[84:87], v[192:195], v[154:157], v[84:87]
	v_exp_f32_e32 v120, v120
	ds_read_b128 v[192:195], v221 offset:10256
	v_mfma_f32_16x16x32_bf16 v[96:99], v[212:215], v[146:149], v[96:99]
	v_exp_f32_e32 v121, v121
	v_mfma_f32_16x16x32_bf16 v[100:103], v[212:215], v[154:157], v[100:103]
	v_exp_f32_e32 v122, v122
	v_exp_f32_e32 v123, v123
	s_waitcnt lgkmcnt(7)
	v_mfma_f32_16x16x32_bf16 v[32:35], v[196:199], v[150:153], v[32:35]
	v_exp_f32_e32 v124, v124
	v_mfma_f32_16x16x32_bf16 v[36:39], v[196:199], v[158:161], v[36:39]
	v_exp_f32_e32 v125, v125
	ds_read_b128 v[196:199], v220 offset:12304
	s_waitcnt lgkmcnt(7)
	v_mfma_f32_16x16x32_bf16 v[48:51], v[200:203], v[150:153], v[48:51]
	v_exp_f32_e32 v126, v126
	v_mfma_f32_16x16x32_bf16 v[52:55], v[200:203], v[158:161], v[52:55]
	v_exp_f32_e32 v127, v127
	ds_read_b128 v[200:203], v221 offset:12304
	s_waitcnt lgkmcnt(7)
	v_mfma_f32_16x16x32_bf16 v[64:67], v[204:207], v[150:153], v[64:67]
	v_cvt_pk_bf16_f32 v162, v112, v113
	v_cvt_pk_bf16_f32 v163, v114, v115
	v_mfma_f32_16x16x32_bf16 v[68:71], v[204:207], v[158:161], v[68:71]
	v_cvt_pk_bf16_f32 v170, v116, v117
	ds_read_b128 v[204:207], v220 offset:14352
	s_waitcnt lgkmcnt(7)
	v_mfma_f32_16x16x32_bf16 v[80:83], v[208:211], v[150:153], v[80:83]
	v_cvt_pk_bf16_f32 v171, v118, v119
	v_mfma_f32_16x16x32_bf16 v[84:87], v[208:211], v[158:161], v[84:87]
	v_cvt_pk_bf16_f32 v164, v120, v121
	ds_read_b128 v[208:211], v221 offset:14352
	v_mfma_f32_16x16x32_bf16 v[96:99], v[212:215], v[150:153], v[96:99]
	v_cvt_pk_bf16_f32 v165, v122, v123
	v_mfma_f32_16x16x32_bf16 v[100:103], v[212:215], v[158:161], v[100:103]
	v_cvt_pk_bf16_f32 v172, v124, v125
	v_cvt_pk_bf16_f32 v173, v126, v127
	s_waitcnt lgkmcnt(7)
	v_mfma_f32_16x16x32_bf16 v[112:115], v[180:183], v[0:3], v[216:219]
	v_exp_f32_e32 v128, v128
	v_exp_f32_e32 v129, v129
	v_mfma_f32_16x16x32_bf16 v[116:119], v[180:183], v[8:11], v[216:219]
	v_exp_f32_e32 v130, v130
	v_exp_f32_e32 v131, v131
	ds_read_b128 v[180:183], v222 offset:16400
	s_waitcnt lgkmcnt(7)
	v_mfma_f32_16x16x32_bf16 v[112:115], v[184:187], v[4:7], v[112:115]
	v_exp_f32_e32 v132, v132
	v_exp_f32_e32 v133, v133
	v_mfma_f32_16x16x32_bf16 v[116:119], v[184:187], v[12:15], v[116:119]
	v_exp_f32_e32 v134, v134
	v_exp_f32_e32 v135, v135
	ds_read_b128 v[184:187], v222 offset:20496
	s_waitcnt lgkmcnt(7)
	v_mfma_f32_16x16x32_bf16 v[120:123], v[188:191], v[0:3], v[216:219]
	v_exp_f32_e32 v136, v136
	v_exp_f32_e32 v137, v137
	v_cvt_pk_bf16_f32 v166, v128, v129
	v_mfma_f32_16x16x32_bf16 v[124:127], v[188:191], v[8:11], v[216:219]
	v_exp_f32_e32 v138, v138
	v_exp_f32_e32 v139, v139
	v_cvt_pk_bf16_f32 v167, v130, v131
	ds_read_b128 v[188:191], v222 offset:24592
	s_waitcnt lgkmcnt(7)
	v_mfma_f32_16x16x32_bf16 v[120:123], v[192:195], v[4:7], v[120:123]
	v_exp_f32_e32 v140, v140
	v_exp_f32_e32 v141, v141
	v_cvt_pk_bf16_f32 v174, v132, v133
	v_mfma_f32_16x16x32_bf16 v[124:127], v[192:195], v[12:15], v[124:127]
	v_exp_f32_e32 v142, v142
	v_exp_f32_e32 v143, v143
	v_cvt_pk_bf16_f32 v175, v134, v135
	ds_read_b128 v[192:195], v222 offset:28688
	s_waitcnt lgkmcnt(7)
	v_mfma_f32_16x16x32_bf16 v[128:131], v[196:199], v[0:3], v[216:219]
	v_cvt_pk_bf16_f32 v168, v136, v137
	v_mfma_f32_16x16x32_bf16 v[132:135], v[196:199], v[8:11], v[216:219]
	v_cvt_pk_bf16_f32 v169, v138, v139
	ds_read_b128 v[196:199], v223 offset:16400
	s_waitcnt lgkmcnt(7)
	v_mfma_f32_16x16x32_bf16 v[128:131], v[200:203], v[4:7], v[128:131]
	v_cvt_pk_bf16_f32 v176, v140, v141
	v_mfma_f32_16x16x32_bf16 v[132:135], v[200:203], v[12:15], v[132:135]
	v_cvt_pk_bf16_f32 v177, v142, v143
	ds_read_b128 v[200:203], v223 offset:20496
	s_waitcnt lgkmcnt(7)
	v_mfma_f32_16x16x32_bf16 v[136:139], v[204:207], v[0:3], v[216:219]
	v_mfma_f32_16x16x32_bf16 v[140:143], v[204:207], v[8:11], v[216:219]
	ds_read_b128 v[204:207], v223 offset:24592
	s_waitcnt lgkmcnt(7)
	v_mfma_f32_16x16x32_bf16 v[136:139], v[208:211], v[4:7], v[136:139]
	v_mfma_f32_16x16x32_bf16 v[140:143], v[208:211], v[12:15], v[140:143]
	ds_read_b128 v[208:211], v223 offset:28688
	s_waitcnt lgkmcnt(7)
	v_mfma_f32_16x16x32_bf16 v[40:43], v[180:183], v[162:165], v[40:43]
	v_exp_f32_e32 v112, v112
	v_mfma_f32_16x16x32_bf16 v[44:47], v[180:183], v[170:173], v[44:47]
	v_exp_f32_e32 v113, v113
	ds_read_b128 v[180:183], v220 offset:8208
	s_waitcnt lgkmcnt(7)
	v_mfma_f32_16x16x32_bf16 v[56:59], v[184:187], v[162:165], v[56:59]
	v_exp_f32_e32 v114, v114
	v_mfma_f32_16x16x32_bf16 v[60:63], v[184:187], v[170:173], v[60:63]
	v_exp_f32_e32 v115, v115
	ds_read_b128 v[184:187], v221 offset:8208
	s_waitcnt lgkmcnt(7)
	v_mfma_f32_16x16x32_bf16 v[72:75], v[188:191], v[162:165], v[72:75]
	v_exp_f32_e32 v116, v116
	v_exp_f32_e32 v117, v117
	v_mfma_f32_16x16x32_bf16 v[76:79], v[188:191], v[170:173], v[76:79]
	v_exp_f32_e32 v118, v118
	ds_read_b128 v[188:191], v220 offset:10256
	s_waitcnt lgkmcnt(7)
	v_mfma_f32_16x16x32_bf16 v[88:91], v[192:195], v[162:165], v[88:91]
	v_exp_f32_e32 v119, v119
	v_mfma_f32_16x16x32_bf16 v[92:95], v[192:195], v[170:173], v[92:95]
	v_exp_f32_e32 v120, v120
	ds_read_b128 v[192:195], v221 offset:10256
	v_mfma_f32_16x16x32_bf16 v[104:107], v[212:215], v[162:165], v[104:107]
	v_exp_f32_e32 v121, v121
	v_mfma_f32_16x16x32_bf16 v[108:111], v[212:215], v[170:173], v[108:111]
	v_exp_f32_e32 v122, v122
	v_exp_f32_e32 v123, v123
	s_waitcnt lgkmcnt(7)
	v_mfma_f32_16x16x32_bf16 v[40:43], v[196:199], v[166:169], v[40:43]
	v_exp_f32_e32 v124, v124
	v_mfma_f32_16x16x32_bf16 v[44:47], v[196:199], v[174:177], v[44:47]
	v_exp_f32_e32 v125, v125
	ds_read_b128 v[196:199], v220 offset:12304
	s_waitcnt lgkmcnt(7)
	v_mfma_f32_16x16x32_bf16 v[56:59], v[200:203], v[166:169], v[56:59]
	v_exp_f32_e32 v126, v126
	v_mfma_f32_16x16x32_bf16 v[60:63], v[200:203], v[174:177], v[60:63]
	v_exp_f32_e32 v127, v127
	ds_read_b128 v[200:203], v221 offset:12304
	s_waitcnt lgkmcnt(7)
	v_mfma_f32_16x16x32_bf16 v[72:75], v[204:207], v[166:169], v[72:75]
	v_cvt_pk_bf16_f32 v146, v112, v113
	v_cvt_pk_bf16_f32 v147, v114, v115
	v_mfma_f32_16x16x32_bf16 v[76:79], v[204:207], v[174:177], v[76:79]
	v_cvt_pk_bf16_f32 v154, v116, v117
	ds_read_b128 v[204:207], v220 offset:14352
	s_waitcnt lgkmcnt(7)
	v_mfma_f32_16x16x32_bf16 v[88:91], v[208:211], v[166:169], v[88:91]
	v_cvt_pk_bf16_f32 v155, v118, v119
	v_mfma_f32_16x16x32_bf16 v[92:95], v[208:211], v[174:177], v[92:95]
	v_cvt_pk_bf16_f32 v148, v120, v121
	ds_read_b128 v[208:211], v221 offset:14352
	v_mfma_f32_16x16x32_bf16 v[104:107], v[212:215], v[166:169], v[104:107]
	v_cvt_pk_bf16_f32 v149, v122, v123
	v_mfma_f32_16x16x32_bf16 v[108:111], v[212:215], v[174:177], v[108:111]
	v_cvt_pk_bf16_f32 v156, v124, v125
	v_cvt_pk_bf16_f32 v157, v126, v127
	s_waitcnt lgkmcnt(7)
	v_mfma_f32_16x16x32_bf16 v[112:115], v[180:183], v[16:19], v[216:219]
	v_exp_f32_e32 v128, v128
	v_exp_f32_e32 v129, v129
	v_mfma_f32_16x16x32_bf16 v[116:119], v[180:183], v[24:27], v[216:219]
	v_exp_f32_e32 v130, v130
	v_exp_f32_e32 v131, v131
	ds_read_b128 v[180:183], v232 offset:16400
	s_waitcnt lgkmcnt(7)
	v_mfma_f32_16x16x32_bf16 v[112:115], v[184:187], v[20:23], v[112:115]
	v_exp_f32_e32 v132, v132
	v_exp_f32_e32 v133, v133
	v_mfma_f32_16x16x32_bf16 v[116:119], v[184:187], v[28:31], v[116:119]
	v_exp_f32_e32 v134, v134
	v_exp_f32_e32 v135, v135
	ds_read_b128 v[184:187], v232 offset:20496
	s_waitcnt lgkmcnt(7)
	v_mfma_f32_16x16x32_bf16 v[120:123], v[188:191], v[16:19], v[216:219]
	v_exp_f32_e32 v136, v136
	v_exp_f32_e32 v137, v137
	v_cvt_pk_bf16_f32 v150, v128, v129
	v_mfma_f32_16x16x32_bf16 v[124:127], v[188:191], v[24:27], v[216:219]
	v_exp_f32_e32 v138, v138
	v_exp_f32_e32 v139, v139
	v_cvt_pk_bf16_f32 v151, v130, v131
	ds_read_b128 v[188:191], v232 offset:24592
	s_waitcnt lgkmcnt(7)
	v_mfma_f32_16x16x32_bf16 v[120:123], v[192:195], v[20:23], v[120:123]
	v_exp_f32_e32 v140, v140
	v_exp_f32_e32 v141, v141
	v_cvt_pk_bf16_f32 v158, v132, v133
	v_mfma_f32_16x16x32_bf16 v[124:127], v[192:195], v[28:31], v[124:127]
	v_exp_f32_e32 v142, v142
	v_exp_f32_e32 v143, v143
	v_cvt_pk_bf16_f32 v159, v134, v135
	ds_read_b128 v[192:195], v232 offset:28688
	s_waitcnt lgkmcnt(7)
	v_mfma_f32_16x16x32_bf16 v[128:131], v[196:199], v[16:19], v[216:219]
	v_cvt_pk_bf16_f32 v152, v136, v137
	v_mfma_f32_16x16x32_bf16 v[132:135], v[196:199], v[24:27], v[216:219]
	v_cvt_pk_bf16_f32 v153, v138, v139
	ds_read_b128 v[196:199], v233 offset:16400
	s_waitcnt lgkmcnt(7)
	v_mfma_f32_16x16x32_bf16 v[128:131], v[200:203], v[20:23], v[128:131]
	v_cvt_pk_bf16_f32 v160, v140, v141
	v_mfma_f32_16x16x32_bf16 v[132:135], v[200:203], v[28:31], v[132:135]
	v_cvt_pk_bf16_f32 v161, v142, v143
	ds_read_b128 v[200:203], v233 offset:20496
	s_waitcnt lgkmcnt(7)
	v_mfma_f32_16x16x32_bf16 v[136:139], v[204:207], v[16:19], v[216:219]
	v_mfma_f32_16x16x32_bf16 v[140:143], v[204:207], v[24:27], v[216:219]
	ds_read_b128 v[204:207], v233 offset:24592
	s_waitcnt lgkmcnt(7)
	v_mfma_f32_16x16x32_bf16 v[136:139], v[208:211], v[20:23], v[136:139]
	v_mfma_f32_16x16x32_bf16 v[140:143], v[208:211], v[28:31], v[140:143]
	ds_read_b128 v[208:211], v233 offset:28688
	s_cmp_lt_u32 s7, 14
	s_cbranch_scc0 .Lgq_w0
	s_waitcnt vmcnt(4)
	s_branch .Lgq_w1

.Lgq_w1:
	s_barrier
	s_cmp_lt_u32 s7, 13
	s_cbranch_scc0 .Lgq_nodma
	s_lshl_b32 s20, s8, 15
	s_add_u32 s20, s20, s22
	s_mov_b32 m0, s20
	s_add_u32 s21, s20, 0x400
	global_load_lds_dwordx4 v234, s[0:1]
	s_mov_b32 m0, s21
	s_add_u32 s21, s20, 0x4000
	global_load_lds_dwordx4 v235, s[0:1]
	s_mov_b32 m0, s21
	s_add_u32 s21, s20, 0x4400
	global_load_lds_dwordx4 v236, s[2:3]
	s_mov_b32 m0, s21
	s_add_u32 s0, s0, 0x10000
	global_load_lds_dwordx4 v237, s[2:3]
	s_addc_u32 s1, s1, 0
	s_add_u32 s2, s2, 0x100
	s_addc_u32 s3, s3, 0
	s_add_u32 s8, s8, 1
	s_and_b32 s8, s8, 3
.Lgq_nodma:
	v_add_u32_e32 v220, 0x8000, v220
	v_and_b32_e32 v220, 0x1ffff, v220
	v_add_u32_e32 v221, 0x8000, v221
	v_and_b32_e32 v221, 0x1ffff, v221
	s_waitcnt lgkmcnt(7)
	v_mfma_f32_16x16x32_bf16 v[32:35], v[180:183], v[146:149], v[32:35]
	v_exp_f32_e32 v112, v112
	v_mfma_f32_16x16x32_bf16 v[36:39], v[180:183], v[154:157], v[36:39]
	v_exp_f32_e32 v113, v113
	ds_read_b128 v[180:183], v220 offset:16
	s_waitcnt lgkmcnt(7)
	v_mfma_f32_16x16x32_bf16 v[48:51], v[184:187], v[146:149], v[48:51]
	v_exp_f32_e32 v114, v114
	v_mfma_f32_16x16x32_bf16 v[52:55], v[184:187], v[154:157], v[52:55]
	v_exp_f32_e32 v115, v115
	ds_read_b128 v[184:187], v221 offset:16
	s_waitcnt lgkmcnt(7)
	v_mfma_f32_16x16x32_bf16 v[64:67], v[188:191], v[146:149], v[64:67]
	v_exp_f32_e32 v116, v116
	v_exp_f32_e32 v117, v117
	v_mfma_f32_16x16x32_bf16 v[68:71], v[188:191], v[154:157], v[68:71]
	v_exp_f32_e32 v118, v118
	ds_read_b128 v[188:191], v220 offset:2064
	s_waitcnt lgkmcnt(7)
	v_mfma_f32_16x16x32_bf16 v[80:83], v[192:195], v[146:149], v[80:83]
	v_exp_f32_e32 v119, v119
	v_mfma_f32_16x16x32_bf16 v[84:87], v[192:195], v[154:157], v[84:87]
	v_exp_f32_e32 v120, v120
	ds_read_b128 v[192:195], v221 offset:2064
	v_mfma_f32_16x16x32_bf16 v[96:99], v[212:215], v[146:149], v[96:99]
	v_exp_f32_e32 v121, v121
	v_mfma_f32_16x16x32_bf16 v[100:103], v[212:215], v[154:157], v[100:103]
	v_exp_f32_e32 v122, v122
	v_exp_f32_e32 v123, v123
	s_waitcnt lgkmcnt(7)
	v_mfma_f32_16x16x32_bf16 v[32:35], v[196:199], v[150:153], v[32:35]
	v_exp_f32_e32 v124, v124
	v_mfma_f32_16x16x32_bf16 v[36:39], v[196:199], v[158:161], v[36:39]
	v_exp_f32_e32 v125, v125
	ds_read_b128 v[196:199], v220 offset:4112
	s_waitcnt lgkmcnt(7)
	v_mfma_f32_16x16x32_bf16 v[48:51], v[200:203], v[150:153], v[48:51]
	v_exp_f32_e32 v126, v126
	v_mfma_f32_16x16x32_bf16 v[52:55], v[200:203], v[158:161], v[52:55]
	v_exp_f32_e32 v127, v127
	ds_read_b128 v[200:203], v221 offset:4112
	s_waitcnt lgkmcnt(7)
	v_mfma_f32_16x16x32_bf16 v[64:67], v[204:207], v[150:153], v[64:67]
	v_cvt_pk_bf16_f32 v162, v112, v113
	v_cvt_pk_bf16_f32 v163, v114, v115
	v_mfma_f32_16x16x32_bf16 v[68:71], v[204:207], v[158:161], v[68:71]
	v_cvt_pk_bf16_f32 v170, v116, v117
	ds_read_b128 v[204:207], v220 offset:6160
	s_waitcnt lgkmcnt(7)
	v_mfma_f32_16x16x32_bf16 v[80:83], v[208:211], v[150:153], v[80:83]
	v_cvt_pk_bf16_f32 v171, v118, v119
	v_mfma_f32_16x16x32_bf16 v[84:87], v[208:211], v[158:161], v[84:87]
	v_cvt_pk_bf16_f32 v164, v120, v121
	ds_read_b128 v[208:211], v221 offset:6160
	v_mfma_f32_16x16x32_bf16 v[96:99], v[212:215], v[150:153], v[96:99]
	v_cvt_pk_bf16_f32 v165, v122, v123
	v_mfma_f32_16x16x32_bf16 v[100:103], v[212:215], v[158:161], v[100:103]
	v_cvt_pk_bf16_f32 v172, v124, v125
	v_cvt_pk_bf16_f32 v173, v126, v127
	s_waitcnt lgkmcnt(7)
	v_mfma_f32_16x16x32_bf16 v[112:115], v[180:183], v[0:3], v[216:219]
	v_exp_f32_e32 v128, v128
	v_exp_f32_e32 v129, v129
	v_mfma_f32_16x16x32_bf16 v[116:119], v[180:183], v[8:11], v[216:219]
	v_exp_f32_e32 v130, v130
	v_exp_f32_e32 v131, v131
	ds_read_b128 v[180:183], v232 offset:16400
	s_waitcnt lgkmcnt(7)
	v_mfma_f32_16x16x32_bf16 v[112:115], v[184:187], v[4:7], v[112:115]
	v_exp_f32_e32 v132, v132
	v_exp_f32_e32 v133, v133
	v_mfma_f32_16x16x32_bf16 v[116:119], v[184:187], v[12:15], v[116:119]
	v_exp_f32_e32 v134, v134
	v_exp_f32_e32 v135, v135
	ds_read_b128 v[184:187], v232 offset:20496
	s_waitcnt lgkmcnt(7)
	v_mfma_f32_16x16x32_bf16 v[120:123], v[188:191], v[0:3], v[216:219]
	v_exp_f32_e32 v136, v136
	v_exp_f32_e32 v137, v137
	v_cvt_pk_bf16_f32 v166, v128, v129
	v_mfma_f32_16x16x32_bf16 v[124:127], v[188:191], v[8:11], v[216:219]
	v_exp_f32_e32 v138, v138
	v_exp_f32_e32 v139, v139
	v_cvt_pk_bf16_f32 v167, v130, v131
	ds_read_b128 v[188:191], v232 offset:24592
	s_waitcnt lgkmcnt(7)
	v_mfma_f32_16x16x32_bf16 v[120:123], v[192:195], v[4:7], v[120:123]
	v_exp_f32_e32 v140, v140
	v_exp_f32_e32 v141, v141
	v_cvt_pk_bf16_f32 v174, v132, v133
	v_mfma_f32_16x16x32_bf16 v[124:127], v[192:195], v[12:15], v[124:127]
	v_exp_f32_e32 v142, v142
	v_exp_f32_e32 v143, v143
	v_cvt_pk_bf16_f32 v175, v134, v135
	ds_read_b128 v[192:195], v232 offset:28688
	s_waitcnt lgkmcnt(7)
	v_mfma_f32_16x16x32_bf16 v[128:131], v[196:199], v[0:3], v[216:219]
	v_cvt_pk_bf16_f32 v168, v136, v137
	v_mfma_f32_16x16x32_bf16 v[132:135], v[196:199], v[8:11], v[216:219]
	v_cvt_pk_bf16_f32 v169, v138, v139
	ds_read_b128 v[196:199], v233 offset:16400
	s_waitcnt lgkmcnt(7)
	v_mfma_f32_16x16x32_bf16 v[128:131], v[200:203], v[4:7], v[128:131]
	v_cvt_pk_bf16_f32 v176, v140, v141
	v_mfma_f32_16x16x32_bf16 v[132:135], v[200:203], v[12:15], v[132:135]
	v_cvt_pk_bf16_f32 v177, v142, v143
	ds_read_b128 v[200:203], v233 offset:20496
	s_waitcnt lgkmcnt(7)
	v_mfma_f32_16x16x32_bf16 v[136:139], v[204:207], v[0:3], v[216:219]
	v_mfma_f32_16x16x32_bf16 v[140:143], v[204:207], v[8:11], v[216:219]
	ds_read_b128 v[204:207], v233 offset:24592
	s_waitcnt lgkmcnt(7)
	v_mfma_f32_16x16x32_bf16 v[136:139], v[208:211], v[4:7], v[136:139]
	v_mfma_f32_16x16x32_bf16 v[140:143], v[208:211], v[12:15], v[140:143]
	ds_read_b128 v[208:211], v233 offset:28688
	s_add_u32 s7, s7, 1
	s_cmp_lt_u32 s7, 16
	s_cbranch_scc1 .Lgq_loop
	s_waitcnt lgkmcnt(7)
	v_mfma_f32_16x16x32_bf16 v[40:43], v[180:183], v[162:165], v[40:43]
	v_mfma_f32_16x16x32_bf16 v[44:47], v[180:183], v[170:173], v[44:47]
	s_waitcnt lgkmcnt(6)
	v_mfma_f32_16x16x32_bf16 v[56:59], v[184:187], v[162:165], v[56:59]
	v_mfma_f32_16x16x32_bf16 v[60:63], v[184:187], v[170:173], v[60:63]
	s_waitcnt lgkmcnt(5)
	v_mfma_f32_16x16x32_bf16 v[72:75], v[188:191], v[162:165], v[72:75]
	v_mfma_f32_16x16x32_bf16 v[76:79], v[188:191], v[170:173], v[76:79]
	s_waitcnt lgkmcnt(4)
	v_mfma_f32_16x16x32_bf16 v[88:91], v[192:195], v[162:165], v[88:91]
	v_mfma_f32_16x16x32_bf16 v[92:95], v[192:195], v[170:173], v[92:95]
	v_mfma_f32_16x16x32_bf16 v[104:107], v[212:215], v[162:165], v[104:107]
	v_mfma_f32_16x16x32_bf16 v[108:111], v[212:215], v[170:173], v[108:111]
	s_waitcnt lgkmcnt(3)
	v_mfma_f32_16x16x32_bf16 v[40:43], v[196:199], v[166:169], v[40:43]
	v_mfma_f32_16x16x32_bf16 v[44:47], v[196:199], v[174:177], v[44:47]
	s_waitcnt lgkmcnt(2)
	v_mfma_f32_16x16x32_bf16 v[56:59], v[200:203], v[166:169], v[56:59]
	v_mfma_f32_16x16x32_bf16 v[60:63], v[200:203], v[174:177], v[60:63]
	s_waitcnt lgkmcnt(1)
	v_mfma_f32_16x16x32_bf16 v[72:75], v[204:207], v[166:169], v[72:75]
	v_mfma_f32_16x16x32_bf16 v[76:79], v[204:207], v[174:177], v[76:79]
	s_waitcnt lgkmcnt(0)
	v_mfma_f32_16x16x32_bf16 v[88:91], v[208:211], v[166:169], v[88:91]
	v_mfma_f32_16x16x32_bf16 v[92:95], v[208:211], v[174:177], v[92:95]
	v_mfma_f32_16x16x32_bf16 v[104:107], v[212:215], v[166:169], v[104:107]
	v_mfma_f32_16x16x32_bf16 v[108:111], v[212:215], v[174:177], v[108:111]
	s_nop 7
	s_nop 7
	s_mov_b64 s[30:31], s[18:19]
	v_div_scale_f32 v244, s[20:21], v96, v96, 1.0
	v_rcp_f32_e32 v245, v244
	s_nop 0
	v_fma_f32 v246, -v244, v245, 1.0
	v_fmac_f32_e32 v245, v246, v245
	v_div_scale_f32 v246, vcc, 1.0, v96, 1.0
	v_mul_f32_e32 v247, v246, v245
	v_fma_f32 v248, -v244, v247, v246
	v_fmac_f32_e32 v247, v248, v245
	v_fma_f32 v244, -v244, v247, v246
	v_div_fmas_f32 v244, v244, v245, v247
	v_div_fixup_f32 v249, v244, v96, 1.0
	v_mul_f32_e32 v32, v32, v249
	v_mul_f32_e32 v33, v33, v249
	v_mul_f32_e32 v34, v34, v249
	v_mul_f32_e32 v35, v35, v249
	v_cvt_pk_bf16_f32 v32, v32, v33
	v_cvt_pk_bf16_f32 v33, v34, v35
	global_store_dwordx2 v179, v[32:33], s[30:31]
	v_mul_f32_e32 v48, v48, v249
	v_mul_f32_e32 v49, v49, v249
	v_mul_f32_e32 v50, v50, v249
	v_mul_f32_e32 v51, v51, v249
	v_cvt_pk_bf16_f32 v48, v48, v49
	v_cvt_pk_bf16_f32 v49, v50, v51
	global_store_dwordx2 v179, v[48:49], s[30:31] offset:32
	v_mul_f32_e32 v64, v64, v249
	v_mul_f32_e32 v65, v65, v249
	v_mul_f32_e32 v66, v66, v249
	v_mul_f32_e32 v67, v67, v249
	v_cvt_pk_bf16_f32 v64, v64, v65
	v_cvt_pk_bf16_f32 v65, v66, v67
	global_store_dwordx2 v179, v[64:65], s[30:31] offset:64
	v_mul_f32_e32 v80, v80, v249
	v_mul_f32_e32 v81, v81, v249
	v_mul_f32_e32 v82, v82, v249
	v_mul_f32_e32 v83, v83, v249
	v_cvt_pk_bf16_f32 v80, v80, v81
	v_cvt_pk_bf16_f32 v81, v82, v83
	global_store_dwordx2 v179, v[80:81], s[30:31] offset:96
	s_add_u32 s30, s30, 0x8000
	s_addc_u32 s31, s31, 0
	v_div_scale_f32 v244, s[20:21], v100, v100, 1.0
	v_rcp_f32_e32 v245, v244
	s_nop 0
	v_fma_f32 v246, -v244, v245, 1.0
	v_fmac_f32_e32 v245, v246, v245
	v_div_scale_f32 v246, vcc, 1.0, v100, 1.0
	v_mul_f32_e32 v247, v246, v245
	v_fma_f32 v248, -v244, v247, v246
	v_fmac_f32_e32 v247, v248, v245
	v_fma_f32 v244, -v244, v247, v246
	v_div_fmas_f32 v244, v244, v245, v247
	v_div_fixup_f32 v249, v244, v100, 1.0
	v_mul_f32_e32 v36, v36, v249
	v_mul_f32_e32 v37, v37, v249
	v_mul_f32_e32 v38, v38, v249
	v_mul_f32_e32 v39, v39, v249
	v_cvt_pk_bf16_f32 v36, v36, v37
	v_cvt_pk_bf16_f32 v37, v38, v39
	global_store_dwordx2 v179, v[36:37], s[30:31]
	v_mul_f32_e32 v52, v52, v249
	v_mul_f32_e32 v53, v53, v249
	v_mul_f32_e32 v54, v54, v249
	v_mul_f32_e32 v55, v55, v249
	v_cvt_pk_bf16_f32 v52, v52, v53
	v_cvt_pk_bf16_f32 v53, v54, v55
	global_store_dwordx2 v179, v[52:53], s[30:31] offset:32
	v_mul_f32_e32 v68, v68, v249
	v_mul_f32_e32 v69, v69, v249
	v_mul_f32_e32 v70, v70, v249
	v_mul_f32_e32 v71, v71, v249
	v_cvt_pk_bf16_f32 v68, v68, v69
	v_cvt_pk_bf16_f32 v69, v70, v71
	global_store_dwordx2 v179, v[68:69], s[30:31] offset:64
	v_mul_f32_e32 v84, v84, v249
	v_mul_f32_e32 v85, v85, v249
	v_mul_f32_e32 v86, v86, v249
	v_mul_f32_e32 v87, v87, v249
	v_cvt_pk_bf16_f32 v84, v84, v85
	v_cvt_pk_bf16_f32 v85, v86, v87
	global_store_dwordx2 v179, v[84:85], s[30:31] offset:96
	s_add_u32 s30, s30, 0x8000
	s_addc_u32 s31, s31, 0
	v_div_scale_f32 v244, s[20:21], v104, v104, 1.0
	v_rcp_f32_e32 v245, v244
	s_nop 0
	v_fma_f32 v246, -v244, v245, 1.0
	v_fmac_f32_e32 v245, v246, v245
	v_div_scale_f32 v246, vcc, 1.0, v104, 1.0
	v_mul_f32_e32 v247, v246, v245
	v_fma_f32 v248, -v244, v247, v246
	v_fmac_f32_e32 v247, v248, v245
	v_fma_f32 v244, -v244, v247, v246
	v_div_fmas_f32 v244, v244, v245, v247
	v_div_fixup_f32 v249, v244, v104, 1.0
	v_mul_f32_e32 v40, v40, v249
	v_mul_f32_e32 v41, v41, v249
	v_mul_f32_e32 v42, v42, v249
	v_mul_f32_e32 v43, v43, v249
	v_cvt_pk_bf16_f32 v40, v40, v41
	v_cvt_pk_bf16_f32 v41, v42, v43
	global_store_dwordx2 v179, v[40:41], s[30:31]
	v_mul_f32_e32 v56, v56, v249
	v_mul_f32_e32 v57, v57, v249
	v_mul_f32_e32 v58, v58, v249
	v_mul_f32_e32 v59, v59, v249
	v_cvt_pk_bf16_f32 v56, v56, v57
	v_cvt_pk_bf16_f32 v57, v58, v59
	global_store_dwordx2 v179, v[56:57], s[30:31] offset:32
	v_mul_f32_e32 v72, v72, v249
	v_mul_f32_e32 v73, v73, v249
	v_mul_f32_e32 v74, v74, v249
	v_mul_f32_e32 v75, v75, v249
	v_cvt_pk_bf16_f32 v72, v72, v73
	v_cvt_pk_bf16_f32 v73, v74, v75
	global_store_dwordx2 v179, v[72:73], s[30:31] offset:64
	v_mul_f32_e32 v88, v88, v249
	v_mul_f32_e32 v89, v89, v249
	v_mul_f32_e32 v90, v90, v249
	v_mul_f32_e32 v91, v91, v249
	v_cvt_pk_bf16_f32 v88, v88, v89
	v_cvt_pk_bf16_f32 v89, v90, v91
	global_store_dwordx2 v179, v[88:89], s[30:31] offset:96
	s_add_u32 s30, s30, 0x8000
	s_addc_u32 s31, s31, 0
	v_div_scale_f32 v244, s[20:21], v108, v108, 1.0
	v_rcp_f32_e32 v245, v244
	s_nop 0
	v_fma_f32 v246, -v244, v245, 1.0
	v_fmac_f32_e32 v245, v246, v245
	v_div_scale_f32 v246, vcc, 1.0, v108, 1.0
	v_mul_f32_e32 v247, v246, v245
	v_fma_f32 v248, -v244, v247, v246
	v_fmac_f32_e32 v247, v248, v245
	v_fma_f32 v244, -v244, v247, v246
	v_div_fmas_f32 v244, v244, v245, v247
	v_div_fixup_f32 v249, v244, v108, 1.0
	v_mul_f32_e32 v44, v44, v249
	v_mul_f32_e32 v45, v45, v249
	v_mul_f32_e32 v46, v46, v249
	v_mul_f32_e32 v47, v47, v249
	v_cvt_pk_bf16_f32 v44, v44, v45
	v_cvt_pk_bf16_f32 v45, v46, v47
	global_store_dwordx2 v179, v[44:45], s[30:31]
	v_mul_f32_e32 v60, v60, v249
	v_mul_f32_e32 v61, v61, v249
	v_mul_f32_e32 v62, v62, v249
	v_mul_f32_e32 v63, v63, v249
	v_cvt_pk_bf16_f32 v60, v60, v61
	v_cvt_pk_bf16_f32 v61, v62, v63
	global_store_dwordx2 v179, v[60:61], s[30:31] offset:32
	v_mul_f32_e32 v76, v76, v249
	v_mul_f32_e32 v77, v77, v249
	v_mul_f32_e32 v78, v78, v249
	v_mul_f32_e32 v79, v79, v249
	v_cvt_pk_bf16_f32 v76, v76, v77
	v_cvt_pk_bf16_f32 v77, v78, v79
	global_store_dwordx2 v179, v[76:77], s[30:31] offset:64
	v_mul_f32_e32 v92, v92, v249
	v_mul_f32_e32 v93, v93, v249
	v_mul_f32_e32 v94, v94, v249
	v_mul_f32_e32 v95, v95, v249
	v_cvt_pk_bf16_f32 v92, v92, v93
	v_cvt_pk_bf16_f32 v93, v94, v95
	global_store_dwordx2 v179, v[92:93], s[30:31] offset:96
	s_add_u32 s6, s6, 1
	s_cmp_lt_u32 s6, 2
	s_cbranch_scc1 .Lgq_tile
	s_waitcnt vmcnt(0) lgkmcnt(0)
	v_readlane_b32 s0, v240, 0
	v_readlane_b32 s1, v240, 1
	v_readlane_b32 s2, v240, 2
	v_readlane_b32 s3, v240, 3
	v_readlane_b32 s4, v240, 4
	v_readlane_b32 s5, v240, 5
	v_readlane_b32 s6, v240, 6
	v_readlane_b32 s7, v240, 7
	v_readlane_b32 s8, v240, 8
	v_readlane_b32 s9, v240, 9
	v_readlane_b32 s10, v240, 10
	v_readlane_b32 s11, v240, 11
	v_readlane_b32 s12, v240, 12
	v_readlane_b32 s13, v240, 13
	v_readlane_b32 s14, v240, 14
	v_readlane_b32 s15, v240, 15
	v_readlane_b32 s16, v240, 16
	v_readlane_b32 s17, v240, 17
	v_readlane_b32 s18, v240, 18
	v_readlane_b32 s19, v240, 19
	v_readlane_b32 s20, v240, 20
	v_readlane_b32 s21, v240, 21
	v_readlane_b32 s22, v240, 22
	v_readlane_b32 s23, v240, 23
	v_readlane_b32 s24, v240, 24
	v_readlane_b32 s25, v240, 25
	v_readlane_b32 s26, v240, 26
	v_readlane_b32 s27, v240, 27
	v_readlane_b32 s28, v240, 28
	v_readlane_b32 s29, v240, 29
	v_readlane_b32 s30, v240, 30
	v_readlane_b32 s31, v240, 31
	v_readlane_b32 s32, v240, 32
	v_readlane_b32 s33, v240, 33
	v_readlane_b32 s34, v240, 34
	v_readlane_b32 s35, v240, 35
	v_readlane_b32 s36, v240, 36
	v_readlane_b32 s37, v240, 37
	v_readlane_b32 s38, v240, 38
	v_readlane_b32 s39, v240, 39
	v_readlane_b32 s40, v240, 40
	v_readlane_b32 s41, v240, 41
	v_readlane_b32 s42, v240, 42
	v_readlane_b32 s43, v240, 43
	v_readlane_b32 s44, v240, 44
	v_readlane_b32 s45, v240, 45
	v_readlane_b32 s46, v240, 46
	v_readlane_b32 s47, v240, 47
	v_readlane_b32 s48, v240, 48
	v_readlane_b32 s49, v240, 49
	v_readlane_b32 s50, v240, 50
	v_readlane_b32 s51, v240, 51
	v_readlane_b32 s52, v240, 52
	v_readlane_b32 s53, v240, 53
	v_readlane_b32 s54, v240, 54
	v_readlane_b32 s55, v240, 55
